# KI layout lane-linear + DSA gather TA-friendly lane map with swizzled LDS park and counted vmcnt
# speedup vs baseline: 1.0321x; 1.0321x over previous
; __device__ __forceinline__ unsigned cvt_pk_bf16(float lo, float hi) { const pk_f2_t v = {lo, hi}; return __builtin_bit_cast(unsigned, __builtin_convertvector(v, pk_bf2_t)); }
;     __device__ __forceinline__ void operator()(const pg8::f32x4 (&acc)[2][2][4][2], const pg8::Unit& u, int wr, int wc, int fr, int fq) const {
;     ...
;             else if (pn == 17) { const int c = c0 - 4352;
;                 if (c < 32) { d16 = (bf16*)(ws + WS_KI) + row0 * 32 + c; rs = 32; }
;     ...
;                     const size_t ro = (size_t)(ai * 128 + m * 16) * rs;
;                     if (mode < 2) { pg8::u32x4 w; w.x = pg8::cvt_pk_bf16(v0[0], v0[1]); w.y = pg8::cvt_pk_bf16(v0[2], v0[3]); w.z = pg8::cvt_pk_bf16(v1[0], v1[1]); w.w = pg8::cvt_pk_bf16(v1[2], v1[3]);
;                         *(pg8::u32x4*)(d16 + ro) = w; }
.LBB0_500:
	s_or_saveexec_b64 s[44:45], s[44:45]
	v_mov_b64_e32 v[164:165], 0
	s_mov_b64 s[46:47], 0
	s_xor_b64 exec, exec, s[44:45]
	s_cbranch_execz .LBB0_686
	v_and_b32_e32 v0, 15, v132
	v_lshlrev_b32_e32 v0, 4, v0
	v_lshl_add_u32 v130, v130, 5, v0
	v_and_b32_e32 v132, -16, v132
	v_lshlrev_b64 v[132:133], 6, v[132:133]
	v_lshl_add_u64 v[132:133], s[6:7], 0, v[132:133]
	v_mov_b32_e32 v131, v1
	v_lshl_add_u64 v[132:133], v[130:131], 0, v[132:133]
	s_mov_b64 s[34:35], 0x3757e000
	s_mov_b64 s[46:47], exec
	v_lshl_add_u64 v[164:165], v[132:133], 0, s[34:35]
	v_mov_b64_e32 v[166:167], 32
	v_mov_b32_e32 v176, 1.0
	v_mov_b64_e32 v[162:163], 0
	s_or_b64 s[50:51], s[50:51], exec
	s_or_b64 s[48:49], s[48:49], exec
	s_or_b64 exec, exec, s[44:45]
	s_branch .LBB0_509

; #define GAS __attribute__((address_space(1)))
; #define LAS __attribute__((address_space(3)))
; __device__ __forceinline__ void dsa_token(Frame& F, int b, int t, const bf16* QI, const bf16* KI, const float* WI, const bf16* CKVN, const bf16* QLAT, bf16* OLAT) {
;     const int lane = F.lane, fr = lane & 15, fq = lane >> 4;
;     const size_t row = (size_t)b * SEQ + t;
;     LAS unsigned short* idxl = (LAS unsigned short*)(F.lds + IDXL_OFF + F.wave * 1024);
;     LAS unsigned char* Cb = F.lds + RING_OFF + F.wave * 16384;
;     LAS const float* lut = (LAS const float*)(F.lds + LUTD_OFF) + fr * 128;
;     const int cmax = t >> 6;
;     int nsel;
;     ...
;     for (int rep_i = 0; rep_i < REP_DSA_IDX; ++rep_i)
;     {
;         float sc[64];
;         const bf16x8 qa = *(const GAS bf16x8*)(QI + row * 512 + fr * 32 + 8 * fq);
;         const f32x4 w4 = *(const GAS f32x4*)(WI + row * 16 + 4 * fq);
;         const GAS bf16* kp = (const GAS bf16*)(KI + ((size_t)b * SEQ + fr) * 32 + 8 * fq);
;         bf16x8 kbuf[3][4];
;         float vmax = -INFINITY, vmin = INFINITY;
;     ...
;         const int cmax4 = cmax | 3;
;     ...
;     const GAS char* Cbase = (const GAS char*)(CKVN + (size_t)b * SEQ * 256) + fq * 16;
;     bf16x8 crA[8], crB[8];
;     ...
;     LAS const unsigned char* rb = Cb + ((fr & 3) >> 1) * 256 + (4 * fq + (fr >> 2)) * 16 + (fr & 1) * 8;
.LBB0_942:
	v_readlane_b32 s0, v254, 41
	s_add_i32 s19, s18, s0
	v_and_b32_e32 v6, 15, v107
	s_bitcmp0_b32 s2, 8
	v_lshlrev_b32_e32 v0, 6, v6
	s_cselect_b64 s[20:21], -1, 0
	s_lshl_b32 s0, s18, 14
	v_lshl_add_u64 v[4:5], s[6:7], 0, v[0:1]
	v_and_b32_e32 v0, 48, v176
	s_add_i32 s8, s0, 0
	v_lshl_add_u64 v[4:5], v[4:5], 0, v[0:1]
	s_mov_b64 s[0:1], 0x365a0000
	v_lshl_add_u64 v[180:181], v[4:5], 0, s[0:1]
	v_lshl_add_u64 v[4:5], s[6:7], 0, v[0:1]
	s_mov_b64 s[0:1], 0x376a0000
	v_lshl_add_u64 v[182:183], v[4:5], 0, s[0:1]
	v_readlane_b32 s0, v253, 23
	v_readlane_b32 s1, v253, 24
	v_writelane_b32 v255, s78, 51
	v_mov_b32_e32 v4, s0
	v_mov_b32_e32 v5, s1
	v_lshlrev_b64 v[4:5], 6, v[4:5]
	v_lshl_add_u64 v[4:5], s[6:7], 0, v[4:5]
	v_lshlrev_b32_e32 v8, 4, v176
	v_mov_b32_e32 v9, 0
	v_lshl_add_u64 v[4:5], v[4:5], 0, v[8:9]
	s_mov_b64 s[0:1], 0x375a0000
	v_writelane_b32 v255, s79, 52
	v_lshl_add_u64 v[184:185], v[4:5], 0, s[0:1]
	v_cmp_gt_u32_e64 s[0:1], 16, v176
	v_lshrrev_b32_e32 v7, 4, v176
	v_lshlrev_b32_e32 v2, 9, v6
	v_writelane_b32 v255, s0, 53
	s_lshl_b32 s2, s18, 10
	v_mov_b32_e32 v3, v1
	v_writelane_b32 v255, s1, 54
	v_cmp_eq_u32_e64 s[0:1], 2, v7
	s_sub_i32 s38, 0x1ff, s19
	v_lshlrev_b32_e32 v8, 2, v7
	v_writelane_b32 v255, s0, 55
	v_lshlrev_b32_e32 v178, 3, v7
	v_mov_b32_e32 v179, v1
	v_writelane_b32 v255, s1, 56
	v_lshrrev_b32_e32 v223, 2, v176
	v_lshlrev_b32_e32 v223, 1, v223
	v_readlane_b32 s0, v255, 39
	v_lshlrev_b32_e32 v6, 4, v6
	s_mov_b32 s22, 0
	v_add_u32_e32 v208, s0, v2
	v_cmp_eq_u32_e64 s[0:1], 1, v7
	v_lshl_add_u64 v[2:3], s[6:7], 0, v[2:3]
	v_lshl_add_u32 v7, v7, 8, s8
	v_writelane_b32 v255, s0, 57
	v_or_b32_e32 v177, 64, v176
	v_or_b32_e32 v209, 0x80, v176
	v_writelane_b32 v255, s1, 58
	s_mov_b64 s[0:1], 0x375a1000
	v_lshl_add_u64 v[186:187], v[4:5], 0, s[0:1]
	s_mov_b64 s[0:1], 0x375a1400
	v_lshl_add_u64 v[188:189], v[4:5], 0, s[0:1]
	s_mov_b64 s[0:1], 0x375a1800
	v_lshl_add_u64 v[190:191], v[4:5], 0, s[0:1]
	s_mov_b64 s[0:1], 0x375a1c00
	v_lshl_add_u64 v[192:193], v[4:5], 0, s[0:1]
	s_add_i32 s0, s2, 0
	v_writelane_b32 v253, s0, 22
	s_add_i32 s74, s0, 0x24400
	v_lshl_add_u64 v[4:5], v[2:3], 0, v[0:1]
	s_mov_b64 s[0:1], 0x3faa0000
	v_lshl_add_u64 v[196:197], v[4:5], 0, s[0:1]
	v_readlane_b32 s0, v254, 35
	v_bfe_u32 v5, v107, 2, 2
	v_readlane_b32 s1, v254, 36
	s_add_u32 s0, s6, s0
	v_lshlrev_b32_e32 v4, 7, v176
	v_or_b32_e32 v5, v8, v5
	s_addc_u32 s1, s7, s1
	v_and_b32_e32 v0, 3, v176
	v_lshlrev_b32_e32 v0, 4, v0
	v_and_b32_e32 v4, 0x100, v4
	v_lshlrev_b32_e32 v5, 4, v5
	v_add3_u32 v9, s8, v4, v5
	v_lshl_add_u64 v[4:5], s[0:1], 0, v[0:1]
	s_mov_b64 s[0:1], 0x35da0000
	v_writelane_b32 v253, s19, 18
	v_lshl_add_u64 v[198:199], v[4:5], 0, s[0:1]
	v_lshl_add_u64 v[2:3], v[2:3], 0, v[178:179]
	s_mov_b64 s[0:1], 0x47aa0000
	v_writelane_b32 v253, s20, 19
	v_or_b32_e32 v210, 0xc0, v176
	v_or_b32_e32 v244, 0x940, v176
	v_or_b32_e32 v245, 0x980, v176
	v_or_b32_e32 v246, 0x9c0, v176
	v_or_b32_e32 v247, 0xa00, v176
	v_or_b32_e32 v248, 0xa40, v176
	v_or_b32_e32 v249, 0xa80, v176
	v_or_b32_e32 v250, 0xac0, v176
	v_or_b32_e32 v251, 0xb00, v176
	v_or_b32_e32 v252, 0xb40, v176
	v_or_b32_e32 v204, 0xb80, v176
	v_or_b32_e32 v168, 0xbc0, v176
	v_or_b32_e32 v169, 0xc00, v176
	v_or_b32_e32 v170, 0xc40, v176
	v_or_b32_e32 v171, 0xc80, v176
	v_or_b32_e32 v211, 0xcc0, v176
	v_or_b32_e32 v212, 0xd00, v176
	v_or_b32_e32 v213, 0xd40, v176
	v_or_b32_e32 v214, 0xd80, v176
	v_or_b32_e32 v215, 0xdc0, v176
	v_or_b32_e32 v216, 0xe00, v176
	v_or_b32_e32 v217, 0xe40, v176
	v_or_b32_e32 v218, 0xe80, v176
	v_or_b32_e32 v219, 0xec0, v176
	v_or_b32_e32 v220, 0xf00, v176
	v_or_b32_e32 v221, 0xf40, v176
	v_or_b32_e32 v195, 0xf80, v176
	v_or_b32_e32 v194, 0xfc0, v176
	v_lshl_add_u32 v222, v176, 1, s74
	v_add_u32_e32 v224, s74, v223
	v_lshl_add_u64 v[200:201], v[2:3], 0, s[0:1]
	v_or_b32_e32 v227, 16, v8
	v_add_u32_e32 v226, v9, v118
	v_and_b32_e32 v0, 3, v176
	v_and_b32_e32 v6, 1, v0
	v_bfe_u32 v7, v0, 1, 1
	v_xor_b32_e32 v7, v6, v7
	v_mul_u32_u24_e32 v6, 10, v6
	v_lshl_or_b32 v6, v7, 2, v6
	v_lshrrev_b32_e32 v7, 2, v176
	v_xor_b32_e32 v6, v7, v6
	v_lshl_add_u32 v225, v0, 8, s8
	v_lshl_add_u32 v225, v6, 4, v225
	v_lshrrev_b32_e32 v0, 4, v176
	v_and_b32_e32 v6, 1, v0
	v_bfe_u32 v7, v0, 1, 1
	v_xor_b32_e32 v7, v6, v7
	v_mul_u32_u24_e32 v6, 10, v6
	v_lshl_or_b32 v6, v7, 2, v6
	v_and_b32_e32 v7, 15, v176
	v_xor_b32_e32 v6, v7, v6
	v_lshl_add_u32 v224, v0, 8, s8
	v_lshl_add_u32 v224, v6, 4, v224
	v_bfe_u32 v0, v176, 1, 1
	v_mul_u32_u24_e32 v0, 0xe0, v0
	v_xor_b32_e32 v226, v0, v226
	v_writelane_b32 v253, s21, 20
	s_barrier
	s_branch .LBB0_945

; #define GAS __attribute__((address_space(1)))
; #define DSA_LOADT(cr, hc) do { const GAS char* src_ = Cbase + (size_t)idxl[16 * (hc) + fr] * 512; \
;         _Pragma("unroll") for (int ks = 0; ks < 8; ++ks) cr[ks] = *(const GAS bf16x8*)(src_ + ks * 64); } while (0)
; __device__ __forceinline__ void dsa_token(Frame& F, int b, int t, const bf16* QI, const bf16* KI, const float* WI, const bf16* CKVN, const bf16* QLAT, bf16* OLAT) {
;     ...
;     { const bf16* qp = QLAT + row * 4096 + fr * 256 + 8 * fq;
; #pragma unroll
;       for (int ks = 0; ks < 8; ++ks) qf[ks] = *(const GAS bf16x8*)(qp + 32 * ks); }
;     f32x4 o[16];
; #pragma unroll
;     for (int ct = 0; ct < 16; ++ct) o[ct] = (f32x4){0.f, 0.f, 0.f, 0.f};
;     float m = -1e30f, l = 0.f;
;     const int nhc = (nsel + 15) >> 4;
;     const GAS char* Cbase = (const GAS char*)(CKVN + (size_t)b * SEQ * 256) + fq * 16;
;     bf16x8 crA[8], crB[8];
;     ...
;     DSA_LOADT(crA, 0); if (nhc > 1) DSA_LOADT(crB, 1);
;     for (int hc = 0; hc < nhc; hc += 2) {
.LBB0_1449:
	s_lshl_b64 s[6:7], s[78:79], 13
	v_lshl_add_u64 v[2:3], v[196:197], 0, s[6:7]
	global_load_dwordx4 v[64:67], v[2:3], off
	global_load_dwordx4 v[68:71], v[2:3], off offset:64
	global_load_dwordx4 v[72:75], v[2:3], off offset:128
	global_load_dwordx4 v[76:79], v[2:3], off offset:192
	v_add_u32_e32 v0, s74, v223
	ds_read_u16 v0, v0
	global_load_dwordx4 v[84:87], v[2:3], off offset:256
	global_load_dwordx4 v[88:91], v[2:3], off offset:320
	global_load_dwordx4 v[92:95], v[2:3], off offset:384
	global_load_dwordx4 v[96:99], v[2:3], off offset:448
	s_add_i32 s1, s0, 15
	s_ashr_i32 s1, s1, 4
	s_cmp_lt_i32 s1, 2
	s_waitcnt lgkmcnt(0)
	v_lshlrev_b32_e32 v0, 9, v0
	v_lshl_add_u64 v[2:3], v[198:199], 0, v[0:1]
	global_load_dwordx4 v[100:103], v[2:3], off
	global_load_dwordx4 v[104:107], v[2:3], off offset:64
	global_load_dwordx4 v[108:111], v[2:3], off offset:128
	global_load_dwordx4 v[112:115], v[2:3], off offset:192
	global_load_dwordx4 v[116:119], v[2:3], off offset:256
	global_load_dwordx4 v[120:123], v[2:3], off offset:320
	global_load_dwordx4 v[124:127], v[2:3], off offset:384
	global_load_dwordx4 v[128:131], v[2:3], off offset:448
	s_movk_i32 s84, 0xc0
	s_mov_b32 s85, 0x140000
	s_mov_b64 s[88:89], 0x100000
	s_mov_b64 s[92:93], 0x160000
	s_mov_b64 s[66:67], 0x120000
	s_cbranch_scc1 .LBB0_1451
	v_add_u32_e32 v0, s74, v223
	ds_read_u16 v0, v0 offset:32
	s_waitcnt lgkmcnt(0)
	v_lshlrev_b32_e32 v0, 9, v0
	v_lshl_add_u64 v[2:3], v[198:199], 0, v[0:1]
	global_load_dwordx4 v[132:135], v[2:3], off
	global_load_dwordx4 v[136:139], v[2:3], off offset:64
	global_load_dwordx4 v[140:143], v[2:3], off offset:128
	global_load_dwordx4 v[144:147], v[2:3], off offset:192
	global_load_dwordx4 v[148:151], v[2:3], off offset:256
	global_load_dwordx4 v[152:155], v[2:3], off offset:320
	global_load_dwordx4 v[156:159], v[2:3], off offset:384
	global_load_dwordx4 v[160:163], v[2:3], off offset:448

.LBB0_1455:
	v_add_u32_e32 v230, s7, v178
	v_add_u32_e32 v0, 0x24400, v230
	ds_read_b64 v[2:3], v0
	s_add_i32 s8, s6, -1
	s_add_i32 s100, s6, -2
	s_cmp_ge_i32 s100, s1
	s_cbranch_scc1 .Ldsa_a_lastw
	s_waitcnt vmcnt(15)
	ds_write_b128 v225, v[100:103]
	s_waitcnt vmcnt(14)
	ds_write_b128 v225, v[104:107] offset:1024
	s_waitcnt vmcnt(13)
	ds_write_b128 v225, v[108:111] offset:2048
	s_waitcnt vmcnt(12)
	ds_write_b128 v225, v[112:115] offset:3072
	s_waitcnt vmcnt(11)
	ds_write_b128 v225, v[116:119] offset:4096
	s_waitcnt vmcnt(10)
	ds_write_b128 v225, v[120:123] offset:5120
	s_waitcnt vmcnt(9)
	ds_write_b128 v225, v[124:127] offset:6144
	s_waitcnt vmcnt(8)
	ds_write_b128 v225, v[128:131] offset:7168
	s_branch .Ldsa_a_parked
.Ldsa_a_lastw:
	s_waitcnt vmcnt(7)
	ds_write_b128 v225, v[100:103]
	s_waitcnt vmcnt(6)
	ds_write_b128 v225, v[104:107] offset:1024
	s_waitcnt vmcnt(5)
	ds_write_b128 v225, v[108:111] offset:2048
	s_waitcnt vmcnt(4)
	ds_write_b128 v225, v[112:115] offset:3072
	s_waitcnt vmcnt(3)
	ds_write_b128 v225, v[116:119] offset:4096
	s_waitcnt vmcnt(2)
	ds_write_b128 v225, v[120:123] offset:5120
	s_waitcnt vmcnt(1)
	ds_write_b128 v225, v[124:127] offset:6144
	s_waitcnt vmcnt(0)
	ds_write_b128 v225, v[128:131] offset:7168
.Ldsa_a_parked:
	s_waitcnt lgkmcnt(0)
	ds_read_b128 v[100:103], v224
	ds_read_b128 v[104:107], v224 offset:1024
	ds_read_b128 v[108:111], v224 offset:2048
	ds_read_b128 v[112:115], v224 offset:3072
	ds_read_b128 v[116:119], v224 offset:4096
	ds_read_b128 v[120:123], v224 offset:5120
	ds_read_b128 v[124:127], v224 offset:6144
	ds_read_b128 v[128:131], v224 offset:7168
	s_waitcnt lgkmcnt(7)
	v_mfma_f32_16x16x32_bf16 v[164:167], v[100:103], v[64:67], 0
	s_waitcnt lgkmcnt(6)
	v_mfma_f32_16x16x32_bf16 v[164:167], v[104:107], v[68:71], v[164:167]
	s_waitcnt lgkmcnt(5)
	v_mfma_f32_16x16x32_bf16 v[164:167], v[108:111], v[72:75], v[164:167]
	s_waitcnt lgkmcnt(4)
	v_mfma_f32_16x16x32_bf16 v[164:167], v[112:115], v[76:79], v[164:167]
	s_waitcnt lgkmcnt(3)
	v_mfma_f32_16x16x32_bf16 v[164:167], v[116:119], v[84:87], v[164:167]
	s_waitcnt lgkmcnt(2)
	v_mfma_f32_16x16x32_bf16 v[164:167], v[120:123], v[88:91], v[164:167]
	s_waitcnt lgkmcnt(1)
	v_mfma_f32_16x16x32_bf16 v[164:167], v[124:127], v[92:95], v[164:167]
	s_waitcnt lgkmcnt(0)
	v_mfma_f32_16x16x32_bf16 v[164:167], v[128:131], v[96:99], v[164:167]
	s_cmp_ge_i32 s8, s1
	s_cbranch_scc1 .LBB0_1457
	v_add_u32_e32 v0, s7, v223
	v_add_u32_e32 v0, 0x24440, v0
	ds_read_u16 v0, v0
	s_waitcnt lgkmcnt(0)
	v_lshlrev_b32_e32 v0, 9, v0
	v_lshl_add_u64 v[128:129], v[198:199], 0, v[0:1]
	global_load_dwordx4 v[100:103], v[128:129], off
	global_load_dwordx4 v[104:107], v[128:129], off offset:64
	global_load_dwordx4 v[108:111], v[128:129], off offset:128
	global_load_dwordx4 v[112:115], v[128:129], off offset:192
	global_load_dwordx4 v[116:119], v[128:129], off offset:256
	global_load_dwordx4 v[120:123], v[128:129], off offset:320
	global_load_dwordx4 v[124:127], v[128:129], off offset:384
	s_nop 0
	global_load_dwordx4 v[128:131], v[128:129], off offset:448

.LBB0_1459:
	v_sub_f32_e32 v165, v228, v229
	v_exp_f32_e32 v165, v165
	v_sub_f32_e32 v164, v164, v229
	v_exp_f32_e32 v164, v164
	v_sub_f32_e32 v3, v3, v229
	v_exp_f32_e32 v3, v3
	v_sub_f32_e32 v2, v2, v229
	v_exp_f32_e32 v167, v2
	v_add_f32_e32 v166, 0, v165
	v_add_f32_e32 v166, v164, v166
	v_add_f32_e32 v166, v3, v166
	v_add_f32_e32 v228, v167, v166
	v_fmac_f32_e32 v228, v232, v0
	v_xor_b32_e32 v0, 64, v226
	v_cvt_pk_bf16_f32 v2, v165, v164
	v_cvt_pk_bf16_f32 v3, v3, v167
	ds_read_b64_tr_b16 v[164:165], v226
	ds_read_b64_tr_b16 v[166:167], v0 offset:512
	ds_read_b64_tr_b16 v[232:233], v226 offset:1024
	ds_read_b64_tr_b16 v[234:235], v0 offset:1536
	ds_read_b64_tr_b16 v[236:237], v226 offset:2048
	ds_read_b64_tr_b16 v[238:239], v0 offset:2560
	ds_read_b64_tr_b16 v[240:241], v226 offset:3072
	ds_read_b64_tr_b16 v[242:243], v0 offset:3584
	s_waitcnt lgkmcnt(7)
	v_mfma_f32_16x16x16_bf16 v[80:83], v[164:165], v[2:3], v[80:83]
	s_waitcnt lgkmcnt(6)
	v_mfma_f32_16x16x16_bf16 v[60:63], v[166:167], v[2:3], v[60:63]
	s_waitcnt lgkmcnt(5)
	v_mfma_f32_16x16x16_bf16 v[56:59], v[232:233], v[2:3], v[56:59]
	s_waitcnt lgkmcnt(4)
	v_mfma_f32_16x16x16_bf16 v[52:55], v[234:235], v[2:3], v[52:55]
	s_waitcnt lgkmcnt(3)
	v_mfma_f32_16x16x16_bf16 v[48:51], v[236:237], v[2:3], v[48:51]
	s_waitcnt lgkmcnt(2)
	v_mfma_f32_16x16x16_bf16 v[44:47], v[238:239], v[2:3], v[44:47]
	s_waitcnt lgkmcnt(1)
	v_mfma_f32_16x16x16_bf16 v[40:43], v[240:241], v[2:3], v[40:43]
	s_waitcnt lgkmcnt(0)
	v_mfma_f32_16x16x16_bf16 v[36:39], v[242:243], v[2:3], v[36:39]
	ds_read_b64_tr_b16 v[164:165], v226 offset:4096
	ds_read_b64_tr_b16 v[166:167], v0 offset:4608
	ds_read_b64_tr_b16 v[232:233], v226 offset:5120
	ds_read_b64_tr_b16 v[234:235], v0 offset:5632
	ds_read_b64_tr_b16 v[236:237], v226 offset:6144
	ds_read_b64_tr_b16 v[238:239], v0 offset:6656
	ds_read_b64_tr_b16 v[240:241], v226 offset:7168
	ds_read_b64_tr_b16 v[242:243], v0 offset:7680
	s_waitcnt lgkmcnt(7)
	v_mfma_f32_16x16x16_bf16 v[32:35], v[164:165], v[2:3], v[32:35]
	s_waitcnt lgkmcnt(6)
	v_mfma_f32_16x16x16_bf16 v[28:31], v[166:167], v[2:3], v[28:31]
	s_waitcnt lgkmcnt(5)
	v_mfma_f32_16x16x16_bf16 v[24:27], v[232:233], v[2:3], v[24:27]
	s_waitcnt lgkmcnt(4)
	v_mfma_f32_16x16x16_bf16 v[20:23], v[234:235], v[2:3], v[20:23]
	s_waitcnt lgkmcnt(3)
	v_mfma_f32_16x16x16_bf16 v[16:19], v[236:237], v[2:3], v[16:19]
	s_waitcnt lgkmcnt(2)
	v_mfma_f32_16x16x16_bf16 v[12:15], v[238:239], v[2:3], v[12:15]
	s_waitcnt lgkmcnt(1)
	v_mfma_f32_16x16x16_bf16 v[8:11], v[240:241], v[2:3], v[8:11]
	s_waitcnt lgkmcnt(0)
	v_mfma_f32_16x16x16_bf16 v[4:7], v[242:243], v[2:3], v[4:7]
	s_add_i32 s9, s6, -2
	s_cmp_ge_i32 s9, s1
	s_cbranch_scc1 .LBB0_1453
	v_add_u32_e32 v0, 0x24420, v230
	ds_read_b64 v[2:3], v0
	s_cmp_ge_i32 s8, s1
	s_cbranch_scc1 .Ldsa_b_lastw
	s_waitcnt vmcnt(15)
	ds_write_b128 v225, v[132:135]
	s_waitcnt vmcnt(14)
	ds_write_b128 v225, v[136:139] offset:1024
	s_waitcnt vmcnt(13)
	ds_write_b128 v225, v[140:143] offset:2048
	s_waitcnt vmcnt(12)
	ds_write_b128 v225, v[144:147] offset:3072
	s_waitcnt vmcnt(11)
	ds_write_b128 v225, v[148:151] offset:4096
	s_waitcnt vmcnt(10)
	ds_write_b128 v225, v[152:155] offset:5120
	s_waitcnt vmcnt(9)
	ds_write_b128 v225, v[156:159] offset:6144
	s_waitcnt vmcnt(8)
	ds_write_b128 v225, v[160:163] offset:7168
	s_branch .Ldsa_b_parked
.Ldsa_b_lastw:
	s_waitcnt vmcnt(7)
	ds_write_b128 v225, v[132:135]
	s_waitcnt vmcnt(6)
	ds_write_b128 v225, v[136:139] offset:1024
	s_waitcnt vmcnt(5)
	ds_write_b128 v225, v[140:143] offset:2048
	s_waitcnt vmcnt(4)
	ds_write_b128 v225, v[144:147] offset:3072
	s_waitcnt vmcnt(3)
	ds_write_b128 v225, v[148:151] offset:4096
	s_waitcnt vmcnt(2)
	ds_write_b128 v225, v[152:155] offset:5120
	s_waitcnt vmcnt(1)
	ds_write_b128 v225, v[156:159] offset:6144
	s_waitcnt vmcnt(0)
	ds_write_b128 v225, v[160:163] offset:7168
.Ldsa_b_parked:
	s_waitcnt lgkmcnt(0)
	ds_read_b128 v[132:135], v224
	ds_read_b128 v[136:139], v224 offset:1024
	ds_read_b128 v[140:143], v224 offset:2048
	ds_read_b128 v[144:147], v224 offset:3072
	ds_read_b128 v[148:151], v224 offset:4096
	ds_read_b128 v[152:155], v224 offset:5120
	ds_read_b128 v[156:159], v224 offset:6144
	ds_read_b128 v[160:163], v224 offset:7168
	s_waitcnt lgkmcnt(7)
	v_mfma_f32_16x16x32_bf16 v[164:167], v[132:135], v[64:67], 0
	s_waitcnt lgkmcnt(6)
	v_mfma_f32_16x16x32_bf16 v[164:167], v[136:139], v[68:71], v[164:167]
	s_waitcnt lgkmcnt(5)
	v_mfma_f32_16x16x32_bf16 v[164:167], v[140:143], v[72:75], v[164:167]
	s_waitcnt lgkmcnt(4)
	v_mfma_f32_16x16x32_bf16 v[164:167], v[144:147], v[76:79], v[164:167]
	s_waitcnt lgkmcnt(3)
	v_mfma_f32_16x16x32_bf16 v[164:167], v[148:151], v[84:87], v[164:167]
	s_waitcnt lgkmcnt(2)
	v_mfma_f32_16x16x32_bf16 v[164:167], v[152:155], v[88:91], v[164:167]
	s_waitcnt lgkmcnt(1)
	v_mfma_f32_16x16x32_bf16 v[164:167], v[156:159], v[92:95], v[164:167]
	s_waitcnt lgkmcnt(0)
	v_mfma_f32_16x16x32_bf16 v[164:167], v[160:163], v[96:99], v[164:167]
	s_cmp_ge_i32 s6, s1
	s_cbranch_scc1 .LBB0_1462
	v_add_u32_e32 v0, s7, v223
	v_add_u32_e32 v0, 0x24460, v0
	ds_read_u16 v0, v0
	s_waitcnt lgkmcnt(0)
	v_lshlrev_b32_e32 v0, 9, v0
	v_lshl_add_u64 v[160:161], v[198:199], 0, v[0:1]
	global_load_dwordx4 v[132:135], v[160:161], off
	global_load_dwordx4 v[136:139], v[160:161], off offset:64
	global_load_dwordx4 v[140:143], v[160:161], off offset:128
	global_load_dwordx4 v[144:147], v[160:161], off offset:192
	global_load_dwordx4 v[148:151], v[160:161], off offset:256
	global_load_dwordx4 v[152:155], v[160:161], off offset:320
	global_load_dwordx4 v[156:159], v[160:161], off offset:384
	s_nop 0
	global_load_dwordx4 v[160:163], v[160:161], off offset:448

.LBB0_1464:
	v_sub_f32_e32 v165, v230, v231
	v_exp_f32_e32 v165, v165
	v_sub_f32_e32 v164, v164, v231
	v_exp_f32_e32 v164, v164
	v_sub_f32_e32 v3, v3, v231
	v_exp_f32_e32 v3, v3
	v_sub_f32_e32 v2, v2, v231
	v_exp_f32_e32 v167, v2
	v_add_f32_e32 v166, 0, v165
	v_add_f32_e32 v166, v164, v166
	v_add_f32_e32 v166, v3, v166
	v_add_f32_e32 v232, v167, v166
	v_fmac_f32_e32 v232, v228, v0
	v_xor_b32_e32 v0, 64, v226
	v_cvt_pk_bf16_f32 v2, v165, v164
	v_cvt_pk_bf16_f32 v3, v3, v167
	ds_read_b64_tr_b16 v[164:165], v226
	ds_read_b64_tr_b16 v[166:167], v0 offset:512
	ds_read_b64_tr_b16 v[228:229], v226 offset:1024
	ds_read_b64_tr_b16 v[234:235], v0 offset:1536
	ds_read_b64_tr_b16 v[236:237], v226 offset:2048
	ds_read_b64_tr_b16 v[238:239], v0 offset:2560
	ds_read_b64_tr_b16 v[240:241], v226 offset:3072
	ds_read_b64_tr_b16 v[242:243], v0 offset:3584
	s_waitcnt lgkmcnt(7)
	v_mfma_f32_16x16x16_bf16 v[80:83], v[164:165], v[2:3], v[80:83]
	s_waitcnt lgkmcnt(6)
	v_mfma_f32_16x16x16_bf16 v[60:63], v[166:167], v[2:3], v[60:63]
	s_waitcnt lgkmcnt(5)
	v_mfma_f32_16x16x16_bf16 v[56:59], v[228:229], v[2:3], v[56:59]
	s_waitcnt lgkmcnt(4)
	v_mfma_f32_16x16x16_bf16 v[52:55], v[234:235], v[2:3], v[52:55]
	s_waitcnt lgkmcnt(3)
	v_mfma_f32_16x16x16_bf16 v[48:51], v[236:237], v[2:3], v[48:51]
	s_waitcnt lgkmcnt(2)
	v_mfma_f32_16x16x16_bf16 v[44:47], v[238:239], v[2:3], v[44:47]
	s_waitcnt lgkmcnt(1)
	v_mfma_f32_16x16x16_bf16 v[40:43], v[240:241], v[2:3], v[40:43]
	s_waitcnt lgkmcnt(0)
	v_mfma_f32_16x16x16_bf16 v[36:39], v[242:243], v[2:3], v[36:39]
	ds_read_b64_tr_b16 v[164:165], v226 offset:4096
	ds_read_b64_tr_b16 v[166:167], v0 offset:4608
	ds_read_b64_tr_b16 v[228:229], v226 offset:5120
	ds_read_b64_tr_b16 v[234:235], v0 offset:5632
	ds_read_b64_tr_b16 v[236:237], v226 offset:6144
	ds_read_b64_tr_b16 v[238:239], v0 offset:6656
	ds_read_b64_tr_b16 v[240:241], v226 offset:7168
	ds_read_b64_tr_b16 v[242:243], v0 offset:7680
	s_waitcnt lgkmcnt(7)
	v_mfma_f32_16x16x16_bf16 v[32:35], v[164:165], v[2:3], v[32:35]
	s_waitcnt lgkmcnt(6)
	v_mfma_f32_16x16x16_bf16 v[28:31], v[166:167], v[2:3], v[28:31]
	s_waitcnt lgkmcnt(5)
	v_mfma_f32_16x16x16_bf16 v[24:27], v[228:229], v[2:3], v[24:27]
	s_waitcnt lgkmcnt(4)
	v_mfma_f32_16x16x16_bf16 v[20:23], v[234:235], v[2:3], v[20:23]
	s_waitcnt lgkmcnt(3)
	v_mfma_f32_16x16x16_bf16 v[16:19], v[236:237], v[2:3], v[16:19]
	s_waitcnt lgkmcnt(2)
	v_mfma_f32_16x16x16_bf16 v[12:15], v[238:239], v[2:3], v[12:15]
	s_waitcnt lgkmcnt(1)
	v_mfma_f32_16x16x16_bf16 v[8:11], v[240:241], v[2:3], v[8:11]
	s_waitcnt lgkmcnt(0)
	v_mfma_f32_16x16x16_bf16 v[4:7], v[242:243], v[2:3], v[4:7]
	s_branch .LBB0_1454

; __global__ void __launch_bounds__(NWAVES * 64, 2) mk_fwd(Args args) {
;     extern __shared__ __attribute__((aligned(16))) unsigned char lds[];
	.amdhsa_kernel _Z6mk_fwd4Args
		.amdhsa_group_segment_fixed_size 0
		.amdhsa_private_segment_fixed_size 0
		.amdhsa_kernarg_size 464
		.amdhsa_user_sgpr_count 2
		.amdhsa_user_sgpr_dispatch_ptr 0
		.amdhsa_user_sgpr_queue_ptr 0
		.amdhsa_user_sgpr_kernarg_segment_ptr 1
		.amdhsa_user_sgpr_dispatch_id 0
		.amdhsa_user_sgpr_kernarg_preload_length 0
		.amdhsa_user_sgpr_kernarg_preload_offset 0
		.amdhsa_user_sgpr_private_segment_size 0
		.amdhsa_uses_dynamic_stack 0
		.amdhsa_enable_private_segment 0
		.amdhsa_system_sgpr_workgroup_id_x 1
		.amdhsa_system_sgpr_workgroup_id_y 0
		.amdhsa_system_sgpr_workgroup_id_z 0
		.amdhsa_system_sgpr_workgroup_info 0
		.amdhsa_system_vgpr_workitem_id 0
		.amdhsa_next_free_vgpr 256
		.amdhsa_next_free_sgpr 102
		.amdhsa_accum_offset 256
		.amdhsa_reserve_vcc 1
		.amdhsa_float_round_mode_32 0
		.amdhsa_float_round_mode_16_64 0
		.amdhsa_float_denorm_mode_32 3
		.amdhsa_float_denorm_mode_16_64 3
		.amdhsa_dx10_clamp 1
		.amdhsa_ieee_mode 1
		.amdhsa_fp16_overflow 0
		.amdhsa_tg_split 0
		.amdhsa_exception_fp_ieee_invalid_op 0
		.amdhsa_exception_fp_denorm_src 0
		.amdhsa_exception_fp_ieee_div_zero 0
		.amdhsa_exception_fp_ieee_overflow 0
		.amdhsa_exception_fp_ieee_underflow 0
		.amdhsa_exception_fp_ieee_inexact 0
		.amdhsa_exception_int_div_zero 0
	.end_amdhsa_kernel

; __global__ void __launch_bounds__(NWAVES * 64, 2) mk_fwd(Args args) {
;     extern __shared__ __attribute__((aligned(16))) unsigned char lds[];
amdhsa.kernels:
  - .agpr_count:     0
    .args:
      - .offset:         0
        .size:           208
        .value_kind:     by_value
      - .offset:         208
        .size:           4
        .value_kind:     hidden_block_count_x
      - .offset:         212
        .size:           4
        .value_kind:     hidden_block_count_y
      - .offset:         216
        .size:           4
        .value_kind:     hidden_block_count_z
      - .offset:         220
        .size:           2
        .value_kind:     hidden_group_size_x
      - .offset:         222
        .size:           2
        .value_kind:     hidden_group_size_y
      - .offset:         224
        .size:           2
        .value_kind:     hidden_group_size_z
      - .offset:         226
        .size:           2
        .value_kind:     hidden_remainder_x
      - .offset:         228
        .size:           2
        .value_kind:     hidden_remainder_y
      - .offset:         230
        .size:           2
        .value_kind:     hidden_remainder_z
      - .offset:         248
        .size:           8
        .value_kind:     hidden_global_offset_x
      - .offset:         256
        .size:           8
        .value_kind:     hidden_global_offset_y
      - .offset:         264
        .size:           8
        .value_kind:     hidden_global_offset_z
      - .offset:         272
        .size:           2
        .value_kind:     hidden_grid_dims
      - .offset:         328
        .size:           4
        .value_kind:     hidden_dynamic_lds_size
    .group_segment_fixed_size: 0
    .kernarg_segment_align: 8
    .kernarg_segment_size: 464
    .language:       OpenCL C
    .language_version:
      - 2
      - 0
    .max_flat_workgroup_size: 512
    .name:           _Z6mk_fwd4Args
    .private_segment_fixed_size: 0
    .sgpr_count:     108
    .sgpr_spill_count: 202
    .symbol:         _Z6mk_fwd4Args.kd
    .uniform_work_group_size: 1
    .uses_dynamic_stack: false
    .vgpr_count:     256
    .vgpr_spill_count: 0
    .wavefront_size: 64
